# hand-written attention items (K/V tiles shared by the 4 heads through an LDS-DMA ring); scan partners take attention only
# speedup vs baseline: 1.0288x; 1.0066x over previous
.LBB0_4:
	v_readlane_b32 s11, v227, 0
	s_lshl_b32 s1, s11, 2
	s_lshl_b32 s20, s76, 2
	s_cmpk_lt_i32 s11, 0x2de0
	v_writelane_b32 v227, s1, 9
	s_cselect_b64 s[2:3], -1, 0
	v_writelane_b32 v227, s2, 10
	s_mul_hi_i32 s1, s11, 0x59493e15
	v_mov_b32_e32 v1, 0xb60
	v_writelane_b32 v227, s3, 11
	s_lshr_b32 s2, s1, 31
	s_ashr_i32 s1, s1, 10
	s_add_i32 s2, s1, s2
	s_mul_i32 s1, s2, 0xfffff488
	s_add_i32 s1, s1, s11
	s_cmpk_gt_i32 s1, 0x21f
	s_cselect_b64 s[6:7], -1, 0
	v_writelane_b32 v227, s6, 12
	s_cmpk_gt_u32 s1, 0x31f
	v_sub_co_u32_e32 v1, vcc, s1, v1
	v_writelane_b32 v227, s7, 13
	s_cselect_b64 s[6:7], -1, 0
	v_writelane_b32 v227, s6, 14
	s_cmpk_gt_u32 s1, 0x89f
	v_mov_b32_e32 v2, 0xb68
	v_writelane_b32 v227, s7, 15
	s_cselect_b64 s[6:7], -1, 0
	v_writelane_b32 v227, s6, 16
	s_mul_i32 s0, s77, s76
	s_movk_i32 s77, 0x3ff
	v_writelane_b32 v227, s7, 17
	s_xor_b64 s[6:7], vcc, -1
	v_writelane_b32 v227, s6, 18
	v_sub_co_u32_e32 v2, vcc, s1, v2
	s_nop 0
	v_writelane_b32 v227, s7, 19
	s_xor_b64 s[6:7], vcc, -1
	v_writelane_b32 v227, s6, 20
	s_cmpk_gt_u32 s1, 0xb6f
	s_mov_b32 s89, 0
	v_writelane_b32 v227, s7, 21
	s_cselect_b64 s[6:7], -1, 0
	v_writelane_b32 v227, s6, 22
	s_ashr_i32 s3, s2, 31
	s_lshl_b32 s5, s1, 5
	v_writelane_b32 v227, s7, 23
	s_lshl_b64 s[6:7], s[2:3], 17
	v_writelane_b32 v227, s6, 24
	s_add_i32 s5, s5, 0x7ffe9200
	s_and_b32 s5, s5, 0x7fffffc0
	v_writelane_b32 v227, s7, 25
	s_lshl_b64 s[6:7], s[2:3], 16
	v_writelane_b32 v227, s6, 26
	s_lshl_b32 s8, s2, 1
	s_mov_b64 s[70:71], 0x1000
	v_writelane_b32 v227, s7, 27
	v_writelane_b32 v227, s5, 28
	s_lshl_b32 s5, s11, 6
	s_and_b32 s6, s5, 64
	v_writelane_b32 v227, s6, 29
	v_readfirstlane_b32 s6, v2
	s_lshr_b32 s6, s6, 2
	s_add_i32 s6, s6, s8
	s_ashr_i32 s7, s6, 31
	s_lshl_b64 s[12:13], s[6:7], 16
	v_writelane_b32 v227, s12, 30
	s_lshl_b64 s[6:7], s[6:7], 15
	s_and_b32 s5, s5, 0xc0
	v_writelane_b32 v227, s13, 31
	v_writelane_b32 v227, s6, 32
	s_mov_b64 s[74:75], 0x1200
	v_mov_b32_e32 v154, 0x358637bd
	v_writelane_b32 v227, s7, 33
	v_writelane_b32 v227, s5, 34
	v_readfirstlane_b32 s5, v1
	s_lshr_b32 s5, s5, 2
	s_add_i32 s6, s5, s8
	s_ashr_i32 s7, s6, 31
	s_lshl_b64 s[8:9], s[6:7], 16
	v_writelane_b32 v227, s8, 35
	s_lshl_b64 s[6:7], s[6:7], 15
	s_mul_hi_i32 s5, s2, 0xb00000
	v_writelane_b32 v227, s9, 36
	v_writelane_b32 v227, s6, 37
	v_mov_b32_e32 v1, 0x100
	v_sub_co_u32_e32 v1, vcc, s11, v1
	v_writelane_b32 v227, s7, 38
	v_writelane_b32 v227, s5, 39
	s_mul_i32 s5, s2, 0xb00000
	v_writelane_b32 v227, s5, 40
	s_mul_hi_i32 s5, s2, 0x580000
	v_writelane_b32 v227, s5, 41
	s_mul_i32 s5, s2, 0x580000
	v_writelane_b32 v227, s5, 42
	s_add_i32 s5, s1, 0xf760
	s_and_b32 s6, s5, 0xffff
	s_mul_i32 s6, s6, 0xba2f
	s_lshr_b32 s6, s6, 21
	s_lshl_b32 s7, s6, 6
	s_mul_i32 s6, s6, 44
	s_sub_i32 s5, s5, s6
	s_lshl_b32 s5, s5, 6
	v_writelane_b32 v227, s7, 43
	s_and_b32 s5, s5, 0xffc0
	v_writelane_b32 v227, s5, 44
	s_mul_hi_i32 s5, s2, 0x1600000
	v_writelane_b32 v227, s5, 45
	s_mul_i32 s5, s2, 0x1600000
	v_writelane_b32 v227, s5, 46
	s_lshl_b32 s5, s1, 2
	s_add_i32 s6, s5, 0x7ffff380
	s_and_b32 s6, s6, 0x7fffffc0
	v_writelane_b32 v227, s6, 47
	s_lshl_b32 s6, s1, 6
	s_and_b32 s6, s6, 0x3c0
	v_writelane_b32 v227, s6, 48
	s_lshl_b64 s[6:7], s[2:3], 20
	v_writelane_b32 v227, s6, 49
	s_add_i32 s5, s5, 0x7ffff780
	s_and_b32 s3, s5, 0x7fffffc0
	v_writelane_b32 v227, s7, 50
	v_writelane_b32 v227, s3, 51
	s_mul_hi_i32 s3, s2, 0x880000
	v_writelane_b32 v227, s3, 52
	s_mul_i32 s3, s2, 0x880000
	v_writelane_b32 v227, s3, 53
	s_mul_hi_i32 s3, s2, 0x440000
	v_writelane_b32 v227, s3, 54
	s_mul_i32 s2, s2, 0x440000
	v_writelane_b32 v227, s2, 55
	s_ashr_i32 s2, s1, 31
	s_lshr_b32 s2, s2, 28
	s_add_i32 s2, s1, s2
	s_lshl_b32 s3, s2, 2
	s_and_b32 s2, s2, 0x3fffff0
	s_sub_i32 s1, s1, s2
	s_andn2_b32 s3, s3, 63
	s_lshl_b32 s1, s1, 6
	v_writelane_b32 v227, s3, 56
	s_cmpk_lt_i32 s11, 0x180
	v_writelane_b32 v227, s1, 57
	s_cselect_b64 s[2:3], -1, 0
	s_lshl_b32 s12, s11, 8
	s_lshl_b32 s13, s76, 8
	s_lshr_b32 s14, s11, 3
	v_writelane_b32 v227, s2, 58
	s_cmpk_lt_u32 s11, 0xb00
	s_mov_b32 s26, s13
	v_writelane_b32 v227, s3, 59
	s_cselect_b64 s[2:3], -1, 0
	s_lshl_b32 s1, s11, 3
	v_writelane_b32 v227, s2, 60
	s_and_b32 s30, s1, 56
	s_bfe_u32 s1, s11, 0x30003
	v_writelane_b32 v227, s3, 61
	s_or_b32 s1, s1, s30
	v_writelane_b32 v227, s1, 62
	s_lshr_b32 s1, s11, 6
	v_writelane_b32 v227, s1, 63
	s_lshr_b32 s1, s76, 3
	s_cmpk_lt_u32 s11, 0x200
	v_writelane_b32 v226, s1, 0
	s_cselect_b64 s[2:3], -1, 0
	v_writelane_b32 v226, s2, 1
	s_cmpk_gt_i32 s11, 0x7f
	s_mov_b32 s88, 0x800000
	v_writelane_b32 v226, s3, 2
	s_cselect_b64 s[2:3], -1, 0
	v_writelane_b32 v226, s2, 3
	s_add_i32 s15, s76, 0xffffff80
	s_add_i32 s1, s11, 0xffffff80
	s_and_b32 s5, s11, 0x7fffff80
	v_writelane_b32 v226, s3, 4
	s_and_b64 s[2:3], vcc, exec
	s_cselect_b32 s6, s11, s1
	s_cmpk_lg_i32 s5, 0x100
	s_cselect_b64 s[2:3], -1, 0
	s_cmpk_eq_i32 s5, 0x100
	v_readfirstlane_b32 s5, v1
	s_cselect_b32 s10, s5, s6
	s_cmpk_lg_i32 s76, 0x200
	s_cselect_b64 s[6:7], -1, 0
	s_and_b64 s[8:9], s[6:7], exec
	v_writelane_b32 v226, s15, 5
	s_cselect_b32 s31, s15, 0x180
	s_cselect_b32 s10, s1, s10
	s_mov_b64 s[2:3], -1
	v_writelane_b32 v226, s2, 6
	s_cmpk_lt_i32 s11, 0x100
	v_lshrrev_b32_e32 v1, 20, v0
	v_writelane_b32 v226, s3, 7
	s_cselect_b64 s[2:3], -1, 0
	s_or_b64 s[2:3], s[2:3], s[6:7]
	s_and_b64 s[2:3], s[2:3], exec
	s_cselect_b32 s15, s11, s1
	s_cmpk_lt_u32 s5, 0x80
	s_cselect_b32 s15, s5, s15
	s_cmpk_lt_i32 s15, 0x200
	s_cselect_b64 s[2:3], -1, 0
	s_lshr_b32 s1, s31, 31
	s_add_i32 s1, s31, s1
	s_ashr_i32 s1, s1, 1
	s_movk_i32 s1, 0x100
	s_add_i32 s6, s15, s1
	v_writelane_b32 v226, s2, 8
	s_cmpk_lt_i32 s15, 0x100
	v_lshrrev_b32_e32 v0, 10, v0
	v_writelane_b32 v226, s3, 9
	s_cselect_b64 s[2:3], -1, 0
	v_writelane_b32 v226, s2, 10
	s_cmpk_lt_i32 s15, 0x80
	v_or_b32_e32 v0, v0, v1
	v_writelane_b32 v226, s3, 11
	s_cselect_b64 s[2:3], -1, 0
	v_writelane_b32 v226, s2, 12
	s_bfe_i32 s1, s11, 0x10000
	s_and_b32 s7, s11, 1
	v_writelane_b32 v226, s3, 13
	s_ashr_i32 s2, s11, 5
	s_lshl_b32 s5, s2, 11
	s_and_b32 s3, s1, 0x7ff
	s_lshl_b32 s1, s11, 1
	v_writelane_b32 v226, s5, 14
	s_and_b32 s1, s1, 48
	s_bfe_u32 s8, s11, 0x20001
	s_or_b32 s5, s5, s3
	v_writelane_b32 v226, s1, 15
	s_lshl_b32 s1, s2, 2
	s_cmp_eq_u32 s7, 0
	s_cselect_b32 s16, 1, -1
	v_writelane_b32 v226, s1, 16
	s_mul_i32 s2, s16, 0x300
	v_writelane_b32 v226, s2, 17
	s_mul_i32 s2, s7, 0x900000
	s_mul_i32 s9, s8, 0xc0
	s_or_b32 s2, s2, s9
	v_writelane_b32 v226, s9, 18
	s_addk_i32 s2, 0xff40
	v_writelane_b32 v226, s2, 19
	s_add_i32 s42, s5, 0x1000
	s_mul_i32 s2, s7, 0xc00000
	v_writelane_b32 v226, s2, 20
	s_mul_i32 s5, s42, 0x300
	s_lshl_b32 s83, s16, 3
	v_writelane_b32 v226, s5, 21
	s_add_i32 s5, s83, s42
	s_mul_i32 s9, s5, 0x300
	s_add_i32 s5, s5, s83
	v_writelane_b32 v226, s9, 22
	s_mul_i32 s9, s5, 0x300
	s_add_i32 s5, s5, s83
	v_writelane_b32 v226, s9, 23
	s_mul_i32 s9, s5, 0x300
	s_add_i32 s5, s5, s83
	v_writelane_b32 v226, s9, 24
	s_mulk_i32 s5, 0x300
	s_lshl_b32 s2, s8, 6
	v_writelane_b32 v226, s5, 25
	s_add_i32 s5, s76, s11
	s_cmpk_lt_i32 s11, 0x300
	s_cselect_b64 s[18:19], -1, 0
	v_writelane_b32 v226, s18, 26
	s_cmpk_lt_u32 s11, 0x660
	v_and_or_b32 v0, v0, s77, v131
	v_writelane_b32 v226, s19, 27
	s_cselect_b64 s[18:19], -1, 0
	s_and_b32 s9, s11, 7
	v_writelane_b32 v226, s18, 28
	s_mul_i32 s17, s9, 12
	s_mul_i32 s9, s14, 0xab
	v_writelane_b32 v226, s19, 29
	s_bfe_u32 s9, s9, 0x5000b
	v_writelane_b32 v226, s9, 30
	s_mul_i32 s9, s9, 12
	s_sub_i32 s9, s14, s9
	s_and_b32 s9, s9, 0xff
	v_writelane_b32 v226, s14, 31
	s_add_i32 s9, s17, s9
	v_writelane_b32 v226, s17, 32
	s_cmp_lt_i32 s78, 0
	v_writelane_b32 v226, s9, 33
	s_cselect_b64 s[18:19], -1, 0
	v_writelane_b32 v226, s18, 34
	s_mov_b32 s1, -1
	s_movk_i32 s81, 0x6000
	v_writelane_b32 v226, s19, 35
	v_cmp_eq_u32_e64 s[18:19], 0, v0
	v_cvt_f32_u32_e32 v0, s13
	s_mov_b64 s[24:25], 0x80
	v_writelane_b32 v226, s18, 36
	s_mov_b64 s[36:37], 0x100
	v_rcp_iflag_f32_e32 v0, v0
	v_writelane_b32 v226, s19, 37
	v_readlane_b32 s18, v227, 7
	v_readlane_b32 s19, v227, 8
	s_load_dword s9, s[18:19], 0x230
	s_load_dwordx2 s[22:23], s[18:19], 0x1f8
	v_mul_f32_e32 v0, 0x4f7ffffe, v0
	v_cvt_u32_f32_e32 v0, v0
	s_mov_b64 s[62:63], 0x10080
	s_waitcnt lgkmcnt(0)
	s_mul_i32 s91, s0, s9
	s_add_u32 s40, s22, 0x200
	s_addc_u32 s41, s23, 0
	s_add_u32 s64, s22, 0x1000
	s_addc_u32 s65, s23, 0
	s_add_u32 s38, s22, 0x1100
	s_addc_u32 s39, s23, 0
	s_add_u32 s54, s22, 0x1200
	s_addc_u32 s55, s23, 0
	s_add_u32 s18, s22, 0x1300
	s_addc_u32 s19, s23, 0
	v_writelane_b32 v226, s18, 38
	s_cmp_eq_u32 s4, 15
	s_mov_b64 s[34:35], 0x20080
	v_writelane_b32 v226, s19, 39
	s_cselect_b64 s[18:19], -1, 0
	v_writelane_b32 v226, s18, 40
	s_cmp_eq_u32 s4, 14
	s_mov_b64 s[94:95], 0x30080
	v_writelane_b32 v226, s19, 41
	s_cselect_b64 s[18:19], -1, 0
	v_writelane_b32 v226, s18, 42
	s_cmp_eq_u32 s4, 13
	s_mov_b64 s[96:97], 0x20100
	v_writelane_b32 v226, s19, 43
	s_cselect_b64 s[18:19], -1, 0
	v_writelane_b32 v226, s18, 44
	s_cmp_eq_u32 s4, 12
	s_mov_b64 s[86:87], 0x30100
	v_writelane_b32 v226, s19, 45
	s_cselect_b64 s[18:19], -1, 0
	v_writelane_b32 v226, s18, 46
	s_cmp_eq_u32 s4, 11
	s_mov_b64 s[68:69], 0x40100
	v_writelane_b32 v226, s19, 47
	s_cselect_b64 s[18:19], -1, 0
	v_writelane_b32 v226, s18, 48
	s_cmp_eq_u32 s4, 10
	v_mov_b32_e32 v155, 0x3a27c5ac
	v_writelane_b32 v226, s19, 49
	s_cselect_b64 s[18:19], -1, 0
	v_writelane_b32 v226, s18, 50
	s_cmp_eq_u32 s4, 9
	s_movk_i32 s17, 0xc00
	v_writelane_b32 v226, s19, 51
	s_cselect_b64 s[18:19], -1, 0
	v_writelane_b32 v226, s18, 52
	s_cmp_eq_u32 s4, 8
	s_movk_i32 s82, 0xfefe
	v_writelane_b32 v226, s19, 53
	s_cselect_b64 s[18:19], -1, 0
	v_writelane_b32 v226, s18, 54
	s_cmp_eq_u32 s4, 7
	v_mov_b32_e32 v156, 0x3ca908c9
	v_writelane_b32 v226, s19, 55
	s_cselect_b64 s[18:19], -1, 0
	v_writelane_b32 v226, s18, 56
	s_cmp_eq_u32 s4, 6
	v_mov_b32_e32 v157, 0xbf1f24be
	v_writelane_b32 v226, s19, 57
	s_cselect_b64 s[18:19], -1, 0
	v_writelane_b32 v226, s18, 58
	s_cmp_eq_u32 s4, 5
	v_mov_b32_e32 v158, 0x3e642e9d
	v_writelane_b32 v226, s19, 59
	s_cselect_b64 s[18:19], -1, 0
	v_writelane_b32 v226, s18, 60
	s_cmp_eq_u32 s4, 4
	v_mov_b32_e32 v159, 0x3e91f4c4
	v_writelane_b32 v226, s19, 61
	s_cselect_b64 s[18:19], -1, 0
	v_writelane_b32 v226, s18, 62
	s_cmp_eq_u32 s4, 3
	v_mov_b32_e32 v160, 0x3c0881c4
	v_writelane_b32 v226, s19, 63
	s_cselect_b64 s[18:19], -1, 0
	v_writelane_b32 v225, s18, 0
	s_cmp_eq_u32 s4, 2
	v_mov_b32_e32 v161, 0xbab64f3b
	v_writelane_b32 v225, s19, 1
	s_cselect_b64 s[18:19], -1, 0
	v_writelane_b32 v225, s18, 2
	s_cmp_eq_u32 s4, 1
	s_mov_b32 s80, 0xfffff
	v_writelane_b32 v225, s19, 3
	s_cselect_b64 s[18:19], -1, 0
	v_writelane_b32 v225, s18, 4
	s_cmp_eq_u32 s4, 0
	s_mov_b32 s90, 0x300000
	v_writelane_b32 v225, s19, 5
	s_cselect_b64 s[18:19], -1, 0
	s_lshl_b32 s0, s4, 8
	s_add_u32 s0, s22, s0
	v_writelane_b32 v225, s18, 6
	s_addc_u32 s4, s23, 0
	v_mov_b32_e32 v162, 1
	v_writelane_b32 v225, s19, 7
	s_add_u32 s18, s0, 0x1400
	s_addc_u32 s19, s4, 0
	v_writelane_b32 v225, s18, 8
	v_mov_b32_e32 v163, 0x60
	v_mov_b32_e32 v164, 0x3b3504f3
	v_writelane_b32 v225, s19, 9
	s_add_u32 s18, s0, 0x2400
	s_addc_u32 s19, s4, 0
	v_writelane_b32 v225, s18, 10
	v_bfrev_b32_e32 v165, 60
	v_mov_b32_e32 v166, 0xf149f2ca
	v_writelane_b32 v225, s19, 11
	s_add_u32 s18, s22, 0x3400
	s_addc_u32 s19, s23, 0
	v_writelane_b32 v225, s18, 12
	v_mov_b32_e32 v167, 0x7fc
	v_bfrev_b32_e32 v168, 0.5
	v_writelane_b32 v225, s19, 13
	s_add_u32 s18, s22, 0x3500
	s_addc_u32 s19, s23, 0
	v_writelane_b32 v225, s18, 14
	s_cmpk_lt_u32 s10, 0x200
	s_mov_b64 s[22:23], 0x40080
	v_writelane_b32 v225, s19, 15
	v_writelane_b32 v225, s10, 16
	s_cselect_b64 s[18:19], -1, 0
	v_writelane_b32 v225, s18, 17
	s_lshl_b32 s0, s7, 16
	s_lshl_b32 s4, s8, 14
	v_writelane_b32 v225, s19, 18
	s_or_b32 s0, s0, s4
	v_writelane_b32 v225, s0, 19
	v_writelane_b32 v225, s12, 20
	s_add_i32 s0, s12, s13
	v_writelane_b32 v225, s0, 21
	s_lshl_b32 s0, s76, 10
	v_writelane_b32 v225, s0, 22
	v_writelane_b32 v225, s0, 23
	v_writelane_b32 v225, s0, 24
	v_writelane_b32 v225, s0, 25
	s_mov_b32 s12, s13
	s_mov_b32 s0, s89
	s_and_b64 s[0:1], s[12:13], s[0:1]
	v_writelane_b32 v225, s0, 26
	s_abs_i32 s4, s31
	s_lshl_b32 s33, s76, 9
	v_writelane_b32 v225, s1, 27
	s_sub_i32 s0, 0, s13
	v_mul_lo_u32 v1, s0, v0
	v_mul_hi_u32 v1, v0, v1
	v_add_u32_e32 v133, v0, v1
	v_cvt_f32_u32_e32 v0, s4
	v_writelane_b32 v225, s33, 28
	v_writelane_b32 v225, s33, 29
	s_mov_b32 s1, s13
	v_rcp_iflag_f32_e32 v0, v0
	v_writelane_b32 v225, s0, 30
	s_ashr_i32 s27, s13, 31
	v_mov_b32_e32 v1, 0
	v_mul_f32_e32 v0, 0x4f7ffffe, v0
	v_cvt_u32_f32_e32 v0, v0
	v_writelane_b32 v225, s1, 31
	s_ashr_i32 s0, s6, 31
	s_abs_i32 s1, s6
	s_sub_i32 s6, 0, s4
	v_readfirstlane_b32 s7, v0
	s_mul_i32 s6, s6, s7
	s_mul_hi_u32 s6, s7, s6
	s_add_i32 s7, s7, s6
	s_mul_hi_u32 s6, s1, s7
	s_mul_i32 s6, s6, s4
	v_cvt_f32_u32_e32 v0, s76
	s_sub_i32 s1, s1, s6
	s_sub_i32 s6, s1, s4
	s_cmp_ge_u32 s1, s4
	s_cselect_b32 s1, s6, s1
	v_rcp_iflag_f32_e32 v0, v0
	s_sub_i32 s6, s1, s4
	s_cmp_ge_u32 s1, s4
	s_cselect_b32 s1, s6, s1
	s_xor_b32 s1, s1, s0
	v_mul_f32_e32 v0, 0x4f7ffffe, v0
	s_sub_i32 s10, s1, s0
	v_cvt_u32_f32_e32 v0, v0
	s_cmpk_lt_i32 s10, 0x100
	s_cselect_b64 s[6:7], -1, 0
	v_writelane_b32 v225, s6, 32
	s_sub_i32 s4, 0, s76
	s_mov_b64 s[18:19], 0x50080
	v_writelane_b32 v225, s7, 33
	v_readfirstlane_b32 s6, v0
	s_mul_i32 s4, s4, s6
	s_mul_hi_u32 s4, s6, s4
	s_add_i32 s6, s6, s4
	s_mul_hi_u32 s4, s5, s6
	s_mul_i32 s4, s4, s76
	s_sub_i32 s4, s5, s4
	s_sub_i32 s7, s4, s76
	s_cmp_ge_u32 s4, s76
	s_cselect_b32 s4, s7, s4
	s_sub_i32 s7, s4, s76
	s_cmp_ge_u32 s4, s76
	s_cselect_b32 s4, s7, s4
	s_cmpk_lt_i32 s4, 0xc0
	v_writelane_b32 v225, s4, 34
	s_cselect_b64 s[8:9], -1, 0
	s_abs_i32 s4, s76
	v_cvt_f32_u32_e32 v0, s4
	v_writelane_b32 v225, s8, 35
	s_sub_i32 s7, 0, s4
	v_mov_b32_e32 v169, 0x7f800000
	v_rcp_iflag_f32_e32 v0, v0
	v_writelane_b32 v225, s9, 36
	v_mov_b32_e32 v170, 0x1000
	v_mov_b32_e32 v171, 0xfffff800
	v_mul_f32_e32 v0, 0x4f7ffffe, v0
	v_cvt_u32_f32_e32 v0, v0
	v_mov_b32_e32 v172, 0xffffff00
	v_mov_b32_e32 v173, 0x1800000
	v_mov_b32_e32 v174, 0xffc00000
	v_readfirstlane_b32 s8, v0
	s_mul_i32 s7, s7, s8
	s_mul_hi_u32 s7, s8, s7
	s_add_i32 s8, s8, s7
	s_mul_hi_u32 s7, s8, 0xc0
	s_mul_i32 s7, s7, s4
	s_sub_i32 s7, 0xc0, s7
	s_sub_i32 s9, s7, s4
	s_cmp_ge_u32 s7, s4
	s_cselect_b32 s7, s9, s7
	s_sub_i32 s9, s7, s4
	s_cmp_ge_u32 s7, s4
	s_cselect_b32 s7, s9, s7
	s_sub_i32 s7, s5, s7
	s_mul_hi_u32 s9, s7, s6
	s_mul_i32 s9, s9, s76
	s_sub_i32 s7, s7, s9
	s_sub_i32 s9, s7, s76
	s_cmp_ge_u32 s7, s76
	s_cselect_b32 s7, s9, s7
	s_sub_i32 s9, s7, s76
	s_cmp_ge_u32 s7, s76
	s_cselect_b32 s7, s9, s7
	v_writelane_b32 v225, s7, 37
	s_cmpk_lt_i32 s7, 0xc0
	s_mul_hi_u32 s7, s8, 0x180
	s_mul_i32 s7, s7, s4
	s_cselect_b64 s[12:13], -1, 0
	s_sub_i32 s7, 0x180, s7
	s_sub_i32 s9, s7, s4
	s_cmp_ge_u32 s7, s4
	s_cselect_b32 s7, s9, s7
	s_sub_i32 s9, s7, s4
	s_cmp_ge_u32 s7, s4
	s_cselect_b32 s7, s9, s7
	s_sub_i32 s7, s5, s7
	s_mul_hi_u32 s9, s7, s6
	s_mul_i32 s9, s9, s76
	s_sub_i32 s7, s7, s9
	s_sub_i32 s9, s7, s76
	s_cmp_ge_u32 s7, s76
	s_cselect_b32 s7, s9, s7
	s_sub_i32 s9, s7, s76
	v_writelane_b32 v225, s12, 38
	s_cmp_ge_u32 s7, s76
	s_cselect_b32 s7, s9, s7
	v_writelane_b32 v225, s13, 39
	v_writelane_b32 v225, s7, 40
	s_cmpk_lt_i32 s7, 0xc0
	s_mul_hi_u32 s7, s8, 0x240
	s_mul_i32 s7, s7, s4
	s_cselect_b64 s[12:13], -1, 0
	s_sub_i32 s7, 0x240, s7
	s_sub_i32 s9, s7, s4
	s_cmp_ge_u32 s7, s4
	s_cselect_b32 s7, s9, s7
	s_sub_i32 s9, s7, s4
	s_cmp_ge_u32 s7, s4
	s_cselect_b32 s7, s9, s7
	s_sub_i32 s7, s5, s7
	s_mul_hi_u32 s9, s7, s6
	s_mul_i32 s9, s9, s76
	s_sub_i32 s7, s7, s9
	s_sub_i32 s9, s7, s76
	s_cmp_ge_u32 s7, s76
	s_cselect_b32 s7, s9, s7
	s_sub_i32 s9, s7, s76
	v_writelane_b32 v225, s12, 41
	s_cmp_ge_u32 s7, s76
	s_cselect_b32 s7, s9, s7
	v_writelane_b32 v225, s13, 42
	v_writelane_b32 v225, s7, 43
	s_cmpk_lt_i32 s7, 0xc0
	s_mul_hi_u32 s7, s8, 0x300
	s_mul_i32 s7, s7, s4
	s_cselect_b64 s[12:13], -1, 0
	s_sub_i32 s7, 0x300, s7
	s_sub_i32 s8, s7, s4
	s_cmp_ge_u32 s7, s4
	s_cselect_b32 s7, s8, s7
	s_sub_i32 s8, s7, s4
	s_cmp_ge_u32 s7, s4
	s_cselect_b32 s4, s8, s7
	s_sub_i32 s4, s5, s4
	s_mul_hi_u32 s6, s4, s6
	s_mul_i32 s6, s6, s76
	s_sub_i32 s4, s4, s6
	s_sub_i32 s6, s4, s76
	s_cmp_ge_u32 s4, s76
	s_cselect_b32 s4, s6, s4
	s_sub_i32 s6, s4, s76
	s_cmp_ge_u32 s4, s76
	v_writelane_b32 v225, s12, 44
	s_cselect_b32 s4, s6, s4
	s_cmpk_lt_i32 s4, 0xc0
	v_writelane_b32 v225, s13, 45
	v_writelane_b32 v225, s4, 46
	s_cselect_b64 s[6:7], -1, 0
	v_writelane_b32 v225, s6, 47
	s_lshl_b32 s4, s5, 5
	s_add_i32 s4, s4, 0x7ffe9200
	v_writelane_b32 v225, s7, 48
	v_writelane_b32 v225, s4, 49
	s_lshl_b32 s4, s76, 5
	v_writelane_b32 v225, s4, 50
	s_lshl_b32 s4, s5, 2
	s_add_i32 s4, s4, 0x7ffff380
	v_writelane_b32 v225, s4, 51
	s_lshl_b32 s4, s5, 6
	v_writelane_b32 v225, s4, 52
	s_lshl_b32 s4, s76, 6
	v_writelane_b32 v225, s4, 53
	s_lshl_b64 s[4:5], s[26:27], 2
	v_writelane_b32 v225, s4, 54
	s_lshl_b64 s[28:29], s[26:27], 1
	v_mbcnt_lo_u32_b32 v0, -1, 0
	v_writelane_b32 v225, s5, 55
	s_lshl_b32 s4, s11, 18
	v_writelane_b32 v225, s4, 56
	s_lshl_b32 s4, s76, 20
	s_bitcmp1_b32 s15, 0
	v_writelane_b32 v225, s4, 57
	s_cselect_b64 s[4:5], -1, 0
	v_writelane_b32 v225, s4, 58
	s_bitcmp1_b32 s31, 0
	v_mbcnt_hi_u32_b32 v150, -1, v0
	v_writelane_b32 v225, s5, 59
	s_cselect_b64 s[4:5], -1, 0
	v_writelane_b32 v225, s4, 60
	s_bitcmp1_b32 s10, 0
	v_and_b32_e32 v0, 64, v150
	v_writelane_b32 v225, s5, 61
	v_writelane_b32 v225, s10, 62
	s_cselect_b64 s[4:5], -1, 0
	s_lshl_b32 s1, s1, 5
	s_lshl_b32 s0, s0, 5
	v_writelane_b32 v225, s4, 63
	s_sub_i32 s0, s1, s0
	s_ashr_i32 s21, s20, 31
	v_writelane_b32 v224, s5, 0
	v_writelane_b32 v224, s0, 1
	s_lshl_b32 s0, s31, 5
	v_writelane_b32 v224, s0, 2
	v_writelane_b32 v224, s15, 3
	s_lshl_b32 s0, s15, 5
	v_writelane_b32 v224, s0, 4
	s_or_b32 s0, s3, 0x1000
	v_writelane_b32 v224, s0, 5
	v_writelane_b32 v224, s16, 6
	s_lshl_b32 s0, s16, 5
	v_writelane_b32 v224, s0, 7
	s_lshl_b32 s0, s11, 4
	v_writelane_b32 v224, s0, 8
	s_lshl_b32 s0, s76, 4
	v_writelane_b32 v224, s0, 9
	s_lshl_b64 s[0:1], s[20:21], 2
	v_writelane_b32 v224, s0, 10
	v_xor_b32_e32 v151, 16, v150
	v_add_u32_e32 v152, 64, v0
	v_writelane_b32 v224, s1, 11
	s_lshl_b64 s[0:1], s[20:21], 12
	v_writelane_b32 v224, s0, 12
	v_xor_b32_e32 v153, 32, v150
	s_mov_b64 s[10:11], 0x10100
	v_writelane_b32 v224, s1, 13
	s_mov_b32 s0, s20
	v_writelane_b32 v224, s0, 14
	s_mov_b32 s5, 0x100000
	v_mov_b32_e32 v175, 0x7fc00000
	v_writelane_b32 v224, s1, 15
	s_lshl_b64 s[0:1], s[20:21], 11
	v_writelane_b32 v224, s0, 16
	v_mov_b32_e32 v176, 0x461c4000
	v_mov_b32_e32 v177, 0x37000000
	v_writelane_b32 v224, s1, 17
	s_lshl_b32 s0, s2, 2
	v_writelane_b32 v224, s0, 18
	v_writelane_b32 v224, s30, 19
	v_writelane_b32 v224, s31, 20
	v_writelane_b32 v224, s42, 21
	v_writelane_b32 v224, s83, 22
	v_writelane_b32 v224, s91, 23
	v_writelane_b32 v224, s40, 24
	s_mov_b32 s0, 0x7f800000
	s_mov_b32 s1, 0x18000
	v_writelane_b32 v224, s41, 25
	v_writelane_b32 v224, s64, 26
	v_not_b32_e32 v178, 63
	v_not_b32_e32 v179, 31
	v_writelane_b32 v224, s65, 27
	v_writelane_b32 v224, s54, 28
	v_mov_b32_e32 v130, v1
	v_mov_b32_e32 v132, v1
	v_writelane_b32 v224, s55, 29
	v_writelane_b32 v224, s38, 30
	s_mov_b32 s31, s42
	s_nop 0
	v_writelane_b32 v224, s39, 31
	v_writelane_b32 v224, s28, 32
	s_nop 1
	v_writelane_b32 v224, s29, 33
	s_branch .LBB0_7
